# first PV V-fragment LDS reads hoisted above exp/cvt block in FoX and NSA window loops
# speedup vs baseline: 1.0002x; 1.0002x over previous
.LBB0_299:
	v_add_u32_e32 v224, s61, v116
	v_add3_u32 v224, v224, v112, v117
	ds_read_b64_tr_b16 v[216:217], v224 offset:8192
	ds_read_b64_tr_b16 v[218:219], v224 offset:8704
	ds_read_b64_tr_b16 v[220:221], v224 offset:9216
	ds_read_b64_tr_b16 v[222:223], v224 offset:9728
	v_sub_f32_e32 v63, v63, v124
	v_sub_f32_e32 v62, v62, v124
	v_sub_f32_e32 v61, v61, v124
	v_sub_f32_e32 v60, v60, v124
	v_sub_f32_e32 v59, v59, v124
	v_sub_f32_e32 v58, v58, v124
	v_sub_f32_e32 v57, v57, v124
	v_sub_f32_e32 v56, v56, v124
	v_sub_f32_e32 v55, v55, v124
	v_sub_f32_e32 v54, v54, v124
	v_sub_f32_e32 v53, v53, v124
	v_sub_f32_e32 v52, v52, v124
	v_sub_f32_e32 v51, v51, v124
	v_sub_f32_e32 v50, v50, v124
	v_sub_f32_e32 v49, v49, v124
	v_sub_f32_e32 v48, v48, v124
	v_sub_f32_e32 v126, v47, v124
	v_sub_f32_e32 v127, v46, v124
	v_sub_f32_e32 v128, v45, v124
	v_sub_f32_e32 v129, v44, v124
	v_sub_f32_e32 v130, v43, v124
	v_sub_f32_e32 v131, v42, v124
	v_sub_f32_e32 v132, v41, v124
	v_sub_f32_e32 v133, v40, v124
	v_sub_f32_e32 v47, v39, v124
	v_sub_f32_e32 v39, v38, v124
	v_sub_f32_e32 v38, v37, v124
	v_sub_f32_e32 v37, v36, v124
	v_sub_f32_e32 v36, v35, v124
	v_sub_f32_e32 v35, v34, v124
	v_sub_f32_e32 v34, v33, v124
	v_sub_f32_e32 v33, v32, v124
	v_exp_f32_e32 v32, v48
	v_exp_f32_e32 v40, v33
	v_exp_f32_e32 v33, v49
	v_exp_f32_e32 v41, v34
	v_exp_f32_e32 v34, v50
	v_exp_f32_e32 v42, v35
	v_exp_f32_e32 v35, v51
	v_exp_f32_e32 v43, v36
	v_exp_f32_e32 v36, v52
	v_exp_f32_e32 v44, v37
	v_exp_f32_e32 v37, v53
	v_exp_f32_e32 v45, v38
	v_exp_f32_e32 v38, v54
	v_exp_f32_e32 v46, v39
	v_exp_f32_e32 v39, v55
	v_exp_f32_e32 v47, v47
	v_exp_f32_e32 v48, v56
	v_exp_f32_e32 v50, v133
	v_exp_f32_e32 v49, v57
	v_exp_f32_e32 v51, v132
	v_exp_f32_e32 v52, v58
	v_exp_f32_e32 v54, v131
	v_exp_f32_e32 v53, v59
	v_exp_f32_e32 v55, v130
	v_exp_f32_e32 v56, v60
	v_exp_f32_e32 v58, v129
	v_exp_f32_e32 v57, v61
	v_exp_f32_e32 v60, v62
	v_exp_f32_e32 v62, v127
	v_exp_f32_e32 v61, v63
	v_exp_f32_e32 v63, v126
	v_exp_f32_e32 v59, v128
	v_pk_add_f32 v[126:127], v[52:53], v[54:55]
	v_pk_add_f32 v[128:129], v[34:35], v[42:43]
	v_pk_add_f32 v[130:131], v[60:61], v[62:63]
	v_pk_add_f32 v[132:133], v[38:39], v[46:47]
	v_pk_add_f32 v[134:135], v[48:49], v[50:51]
	v_pk_add_f32 v[136:137], v[32:33], v[40:41]
	v_pk_add_f32 v[138:139], v[56:57], v[58:59]
	v_pk_add_f32 v[140:141], v[36:37], v[44:45]
	v_pk_add_f32 v[134:135], v[136:137], v[134:135]
	v_pk_add_f32 v[138:139], v[140:141], v[138:139]
	v_pk_add_f32 v[130:131], v[132:133], v[130:131]
	v_pk_add_f32 v[126:127], v[128:129], v[126:127]
	v_pk_add_f32 v[128:129], v[134:135], v[138:139]
	v_pk_add_f32 v[126:127], v[126:127], v[130:131]
	v_add_f32_e32 v128, v128, v129
	v_add_f32_e32 v126, v126, v127
	v_add_f32_e32 v126, v128, v126
	v_add_u32_e32 v125, s61, v116
	v_fmac_f32_e32 v126, v122, v123
	v_cvt_pk_bf16_f32 v32, v32, v33
	v_cvt_pk_bf16_f32 v33, v34, v35
	v_cvt_pk_bf16_f32 v34, v36, v37
	v_cvt_pk_bf16_f32 v35, v38, v39
	v_cvt_pk_bf16_f32 v36, v48, v49
	v_cvt_pk_bf16_f32 v37, v52, v53
	v_cvt_pk_bf16_f32 v38, v56, v57
	v_cvt_pk_bf16_f32 v39, v60, v61
	v_cvt_pk_bf16_f32 v40, v40, v41
	v_cvt_pk_bf16_f32 v41, v42, v43
	v_cvt_pk_bf16_f32 v42, v44, v45
	v_cvt_pk_bf16_f32 v43, v46, v47
	v_cvt_pk_bf16_f32 v44, v50, v51
	v_cvt_pk_bf16_f32 v45, v54, v55
	v_cvt_pk_bf16_f32 v46, v58, v59
	v_cvt_pk_bf16_f32 v47, v62, v63
	s_setprio 1
	v_add3_u32 v52, v125, v112, v117
	s_waitcnt lgkmcnt(2)
	v_mfma_f32_32x32x16_bf16 v[0:15], v[32:35], v[216:219], v[0:15]
	ds_read_b64_tr_b16 v[216:217], v52 offset:10240
	ds_read_b64_tr_b16 v[218:219], v52 offset:10752
	s_waitcnt lgkmcnt(2)
	v_mfma_f32_32x32x16_bf16 v[0:15], v[36:39], v[220:223], v[0:15]
	ds_read_b64_tr_b16 v[220:221], v52 offset:11264
	ds_read_b64_tr_b16 v[222:223], v52 offset:11776
	s_waitcnt lgkmcnt(2)
	v_mfma_f32_32x32x16_bf16 v[0:15], v[40:43], v[216:219], v[0:15]
	ds_read_b64_tr_b16 v[216:217], v52 offset:12288
	ds_read_b64_tr_b16 v[218:219], v52 offset:12800
	s_waitcnt lgkmcnt(2)
	v_mfma_f32_32x32x16_bf16 v[0:15], v[44:47], v[220:223], v[0:15]
	ds_read_b64_tr_b16 v[220:221], v52 offset:13312
	ds_read_b64_tr_b16 v[222:223], v52 offset:13824
	s_waitcnt lgkmcnt(2)
	v_mfma_f32_32x32x16_bf16 v[16:31], v[32:35], v[216:219], v[16:31]
	ds_read_b64_tr_b16 v[216:217], v52 offset:14336
	ds_read_b64_tr_b16 v[218:219], v52 offset:14848
	s_waitcnt lgkmcnt(2)
	v_mfma_f32_32x32x16_bf16 v[16:31], v[36:39], v[220:223], v[16:31]
	ds_read_b64_tr_b16 v[220:221], v52 offset:15360
	ds_read_b64_tr_b16 v[222:223], v52 offset:15872
	s_waitcnt lgkmcnt(2)
	v_mfma_f32_32x32x16_bf16 v[16:31], v[40:43], v[216:219], v[16:31]
	s_waitcnt lgkmcnt(0)
	v_mfma_f32_32x32x16_bf16 v[16:31], v[44:47], v[220:223], v[16:31]
	s_setprio 0
	s_mov_b32 s61, 0
	v_mov_b32_e32 v122, v126
	v_mov_b32_e32 v123, v124

.LBB0_4173:
	v_add_u32_e32 v205, s17, v181
	ds_read_b64_tr_b16 v[216:217], v205 offset:8192
	ds_read_b64_tr_b16 v[218:219], v205 offset:8704
	ds_read_b64_tr_b16 v[220:221], v205 offset:9216
	ds_read_b64_tr_b16 v[222:223], v205 offset:9728
	v_sub_f32_e32 v108, v65, v1
	v_sub_f32_e32 v109, v64, v1
	v_sub_f32_e32 v110, v63, v1
	v_sub_f32_e32 v111, v62, v1
	v_sub_f32_e32 v61, v61, v1
	v_sub_f32_e32 v60, v60, v1
	v_sub_f32_e32 v59, v59, v1
	v_sub_f32_e32 v58, v58, v1
	v_sub_f32_e32 v57, v57, v1
	v_sub_f32_e32 v56, v56, v1
	v_sub_f32_e32 v55, v55, v1
	v_sub_f32_e32 v54, v54, v1
	v_sub_f32_e32 v53, v53, v1
	v_sub_f32_e32 v52, v52, v1
	v_sub_f32_e32 v51, v51, v1
	v_sub_f32_e32 v50, v50, v1
	v_sub_f32_e32 v112, v49, v1
	v_sub_f32_e32 v113, v48, v1
	v_sub_f32_e32 v114, v47, v1
	v_sub_f32_e32 v115, v46, v1
	v_sub_f32_e32 v116, v45, v1
	v_sub_f32_e32 v117, v44, v1
	v_sub_f32_e32 v65, v43, v1
	v_sub_f32_e32 v63, v42, v1
	v_sub_f32_e32 v45, v41, v1
	v_sub_f32_e32 v43, v40, v1
	v_sub_f32_e32 v41, v39, v1
	v_sub_f32_e32 v39, v38, v1
	v_sub_f32_e32 v38, v37, v1
	v_sub_f32_e32 v40, v36, v1
	v_sub_f32_e32 v37, v35, v1
	v_sub_f32_e32 v35, v34, v1
	v_exp_f32_e32 v34, v50
	v_exp_f32_e32 v36, v35
	v_exp_f32_e32 v35, v51
	v_exp_f32_e32 v37, v37
	v_exp_f32_e32 v46, v52
	v_exp_f32_e32 v48, v40
	v_exp_f32_e32 v47, v53
	v_exp_f32_e32 v49, v38
	v_exp_f32_e32 v38, v54
	v_exp_f32_e32 v40, v39
	v_exp_f32_e32 v39, v55
	v_exp_f32_e32 v41, v41
	v_exp_f32_e32 v42, v56
	v_exp_f32_e32 v44, v43
	v_exp_f32_e32 v43, v57
	v_exp_f32_e32 v45, v45
	v_exp_f32_e32 v62, v58
	v_exp_f32_e32 v64, v63
	v_exp_f32_e32 v63, v59
	v_exp_f32_e32 v65, v65
	v_exp_f32_e32 v58, v60
	v_exp_f32_e32 v60, v117
	v_exp_f32_e32 v59, v61
	v_exp_f32_e32 v61, v116
	v_exp_f32_e32 v50, v111
	v_exp_f32_e32 v52, v115
	v_exp_f32_e32 v51, v110
	v_exp_f32_e32 v53, v114
	v_exp_f32_e32 v54, v109
	v_exp_f32_e32 v56, v113
	v_exp_f32_e32 v55, v108
	v_exp_f32_e32 v57, v112
	v_cvt_pk_bf16_f32 v108, v34, v35
	v_cvt_pk_bf16_f32 v109, v46, v47
	v_cvt_pk_bf16_f32 v110, v38, v39
	v_cvt_pk_bf16_f32 v111, v42, v43
	v_cvt_pk_bf16_f32 v112, v62, v63
	v_cvt_pk_bf16_f32 v113, v58, v59
	v_cvt_pk_bf16_f32 v114, v50, v51
	v_cvt_pk_bf16_f32 v115, v54, v55
	v_cvt_pk_bf16_f32 v116, v36, v37
	v_cvt_pk_bf16_f32 v117, v48, v49
	v_cvt_pk_bf16_f32 v118, v40, v41
	v_cvt_pk_bf16_f32 v119, v44, v45
	v_cvt_pk_bf16_f32 v120, v64, v65
	v_cvt_pk_bf16_f32 v121, v60, v61
	v_cvt_pk_bf16_f32 v122, v52, v53
	v_cvt_pk_bf16_f32 v123, v56, v57
	s_setprio 1
	v_add_u32_e32 v124, s17, v181
	s_waitcnt lgkmcnt(2)
	v_mfma_f32_32x32x16_bf16 v[2:17], v[108:111], v[216:219], v[2:17]
	ds_read_b64_tr_b16 v[216:217], v124 offset:10240
	ds_read_b64_tr_b16 v[218:219], v124 offset:10752
	s_waitcnt lgkmcnt(2)
	v_mfma_f32_32x32x16_bf16 v[2:17], v[112:115], v[220:223], v[2:17]
	ds_read_b64_tr_b16 v[220:221], v124 offset:11264
	ds_read_b64_tr_b16 v[222:223], v124 offset:11776
	s_waitcnt lgkmcnt(2)
	v_mfma_f32_32x32x16_bf16 v[2:17], v[116:119], v[216:219], v[2:17]
	ds_read_b64_tr_b16 v[216:217], v124 offset:12288
	ds_read_b64_tr_b16 v[218:219], v124 offset:12800
	s_waitcnt lgkmcnt(2)
	v_mfma_f32_32x32x16_bf16 v[2:17], v[120:123], v[220:223], v[2:17]
	ds_read_b64_tr_b16 v[220:221], v124 offset:13312
	ds_read_b64_tr_b16 v[222:223], v124 offset:13824
	s_waitcnt lgkmcnt(2)
	v_mfma_f32_32x32x16_bf16 v[18:33], v[108:111], v[216:219], v[18:33]
	ds_read_b64_tr_b16 v[216:217], v124 offset:14336
	ds_read_b64_tr_b16 v[218:219], v124 offset:14848
	s_waitcnt lgkmcnt(2)
	v_mfma_f32_32x32x16_bf16 v[18:33], v[112:115], v[220:223], v[18:33]
	ds_read_b64_tr_b16 v[220:221], v124 offset:15360
	ds_read_b64_tr_b16 v[222:223], v124 offset:15872
	s_waitcnt lgkmcnt(2)
	v_mfma_f32_32x32x16_bf16 v[18:33], v[116:119], v[216:219], v[18:33]
	s_waitcnt lgkmcnt(0)
	v_mfma_f32_32x32x16_bf16 v[18:33], v[120:123], v[220:223], v[18:33]
	s_setprio 0
	s_cmp_ge_u32 s13, s48
	s_cselect_b64 s[10:11], -1, 0
	s_and_b64 vcc, exec, s[10:11]
	s_cbranch_vccnz .LBB0_4175
	s_xor_b32 s16, s16, 0x4000
	v_add_u32_e32 v108, s16, v182
	ds_write_b128 v108, v[74:77]
	ds_write_b128 v108, v[78:81] offset:8192
